# P0 GEMV cross-lane reduction: 16 serial bpermute round trips replaced by permlane16/32 swaps, on pd1
# speedup vs baseline: 1.0013x; 1.0001x over previous
; #define LAS __attribute__((address_space(3)))
; template <int LO, int HI> __global__ void __launch_bounds__(NWAVES * 64, 2) fox_fwd(Args args) {
;     ...
; #pragma unroll 8
;             for (int kk = 0; kk < 32; ++kk) { const int k = wave * 128 + 4 * kk + kpar; const float wv = w_ada[(size_t)k * 3072 + col];
;                 const f32x4 c0 = *(const LAS f32x4*)(ct + k * 8), c1 = *(const LAS f32x4*)(ct + k * 8 + 4);
;                 acc[0] += c0[0] * wv; acc[1] += c0[1] * wv; acc[2] += c0[2] * wv; acc[3] += c0[3] * wv; acc[4] += c1[0] * wv; acc[5] += c1[1] * wv; acc[6] += c1[2] * wv; acc[7] += c1[3] * wv; }
; #pragma unroll
;             for (int b = 0; b < 8; ++b) { acc[b] += __shfl_xor(acc[b], 16); acc[b] += __shfl_xor(acc[b], 32); if (lane < 16) red[(wave * 8 + b) * 16 + lane] = acc[b]; }
.LBB0_20:
	v_add_u32_e32 v20, s4, v3
	v_mad_i64_i32 v[18:19], s[14:15], v20, s5, v[14:15]
	global_load_dword v82, v[18:19], off
	v_add_u32_e32 v21, 4, v20
	v_add_u32_e32 v22, 8, v20
	v_add_u32_e32 v23, 12, v20
	v_add_u32_e32 v24, 16, v20
	v_add_u32_e32 v26, 20, v20
	v_add_u32_e32 v28, 24, v20
	v_add_u32_e32 v30, 28, v20
	v_mad_i64_i32 v[18:19], s[14:15], v21, s5, v[14:15]
	v_mad_i64_i32 v[20:21], s[14:15], v22, s5, v[14:15]
	v_mad_i64_i32 v[22:23], s[14:15], v23, s5, v[14:15]
	v_mad_i64_i32 v[24:25], s[14:15], v24, s5, v[14:15]
	v_mad_i64_i32 v[26:27], s[14:15], v26, s5, v[14:15]
	v_mad_i64_i32 v[28:29], s[14:15], v28, s5, v[14:15]
	v_mad_i64_i32 v[30:31], s[14:15], v30, s5, v[14:15]
	global_load_dword v84, v[18:19], off
	global_load_dword v86, v[20:21], off
	global_load_dword v88, v[22:23], off
	global_load_dword v90, v[24:25], off
	global_load_dword v92, v[26:27], off
	global_load_dword v94, v[28:29], off
	global_load_dword v96, v[30:31], off
	ds_read_b128 v[18:21], v17
	ds_read_b128 v[22:25], v17 offset:16
	ds_read_b128 v[26:29], v17 offset:128
	ds_read_b128 v[30:33], v17 offset:144
	ds_read_b128 v[34:37], v17 offset:256
	ds_read_b128 v[38:41], v17 offset:272
	ds_read_b128 v[42:45], v17 offset:384
	ds_read_b128 v[46:49], v17 offset:400
	ds_read_b128 v[50:53], v17 offset:512
	ds_read_b128 v[54:57], v17 offset:528
	ds_read_b128 v[58:61], v17 offset:640
	ds_read_b128 v[62:65], v17 offset:656
	ds_read_b128 v[66:69], v17 offset:768
	ds_read_b128 v[70:73], v17 offset:784
	ds_read_b128 v[74:77], v17 offset:896
	ds_read_b128 v[78:81], v17 offset:912
	s_add_i32 s4, s4, 32
	v_add_u32_e32 v17, 0x400, v17
	s_cmpk_eq_i32 s4, 0x80
	s_waitcnt vmcnt(7) lgkmcnt(14)
	v_pk_fma_f32 v[12:13], v[82:83], v[18:19], v[12:13] op_sel_hi:[0,1,1]
	v_pk_fma_f32 v[10:11], v[82:83], v[20:21], v[10:11] op_sel_hi:[0,1,1]
	v_pk_fma_f32 v[8:9], v[82:83], v[22:23], v[8:9] op_sel_hi:[0,1,1]
	v_pk_fma_f32 v[6:7], v[82:83], v[24:25], v[6:7] op_sel_hi:[0,1,1]
	s_waitcnt vmcnt(6) lgkmcnt(13)
	v_pk_fma_f32 v[12:13], v[84:85], v[26:27], v[12:13] op_sel_hi:[0,1,1]
	v_pk_fma_f32 v[10:11], v[84:85], v[28:29], v[10:11] op_sel_hi:[0,1,1]
	s_waitcnt lgkmcnt(12)
	v_pk_fma_f32 v[8:9], v[84:85], v[30:31], v[8:9] op_sel_hi:[0,1,1]
	v_pk_fma_f32 v[6:7], v[84:85], v[32:33], v[6:7] op_sel_hi:[0,1,1]
	s_waitcnt vmcnt(5) lgkmcnt(11)
	v_pk_fma_f32 v[12:13], v[86:87], v[34:35], v[12:13] op_sel_hi:[0,1,1]
	v_pk_fma_f32 v[10:11], v[86:87], v[36:37], v[10:11] op_sel_hi:[0,1,1]
	s_waitcnt lgkmcnt(10)
	v_pk_fma_f32 v[8:9], v[86:87], v[38:39], v[8:9] op_sel_hi:[0,1,1]
	v_pk_fma_f32 v[6:7], v[86:87], v[40:41], v[6:7] op_sel_hi:[0,1,1]
	s_waitcnt vmcnt(4) lgkmcnt(9)
	v_pk_fma_f32 v[12:13], v[88:89], v[42:43], v[12:13] op_sel_hi:[0,1,1]
	v_pk_fma_f32 v[10:11], v[88:89], v[44:45], v[10:11] op_sel_hi:[0,1,1]
	s_waitcnt lgkmcnt(8)
	v_pk_fma_f32 v[8:9], v[88:89], v[46:47], v[8:9] op_sel_hi:[0,1,1]
	v_pk_fma_f32 v[6:7], v[88:89], v[48:49], v[6:7] op_sel_hi:[0,1,1]
	s_waitcnt vmcnt(3) lgkmcnt(7)
	v_pk_fma_f32 v[12:13], v[90:91], v[50:51], v[12:13] op_sel_hi:[0,1,1]
	v_pk_fma_f32 v[10:11], v[90:91], v[52:53], v[10:11] op_sel_hi:[0,1,1]
	s_waitcnt lgkmcnt(6)
	v_pk_fma_f32 v[8:9], v[90:91], v[54:55], v[8:9] op_sel_hi:[0,1,1]
	v_pk_fma_f32 v[6:7], v[90:91], v[56:57], v[6:7] op_sel_hi:[0,1,1]
	s_waitcnt vmcnt(2) lgkmcnt(5)
	v_pk_fma_f32 v[12:13], v[92:93], v[58:59], v[12:13] op_sel_hi:[0,1,1]
	v_pk_fma_f32 v[10:11], v[92:93], v[60:61], v[10:11] op_sel_hi:[0,1,1]
	s_waitcnt lgkmcnt(4)
	v_pk_fma_f32 v[8:9], v[92:93], v[62:63], v[8:9] op_sel_hi:[0,1,1]
	v_pk_fma_f32 v[6:7], v[92:93], v[64:65], v[6:7] op_sel_hi:[0,1,1]
	s_waitcnt vmcnt(1) lgkmcnt(3)
	v_pk_fma_f32 v[12:13], v[94:95], v[66:67], v[12:13] op_sel_hi:[0,1,1]
	v_pk_fma_f32 v[10:11], v[94:95], v[68:69], v[10:11] op_sel_hi:[0,1,1]
	s_waitcnt lgkmcnt(2)
	v_pk_fma_f32 v[8:9], v[94:95], v[70:71], v[8:9] op_sel_hi:[0,1,1]
	v_pk_fma_f32 v[6:7], v[94:95], v[72:73], v[6:7] op_sel_hi:[0,1,1]
	s_waitcnt vmcnt(0) lgkmcnt(1)
	v_pk_fma_f32 v[12:13], v[96:97], v[74:75], v[12:13] op_sel_hi:[0,1,1]
	v_pk_fma_f32 v[10:11], v[96:97], v[76:77], v[10:11] op_sel_hi:[0,1,1]
	s_waitcnt lgkmcnt(0)
	v_pk_fma_f32 v[8:9], v[96:97], v[78:79], v[8:9] op_sel_hi:[0,1,1]
	v_pk_fma_f32 v[6:7], v[96:97], v[80:81], v[6:7] op_sel_hi:[0,1,1]
	s_cbranch_scc0 .LBB0_20
	v_mbcnt_lo_u32_b32 v3, -1, 0
	v_mbcnt_hi_u32_b32 v14, -1, v3
	v_and_b32_e32 v15, 64, v14
	v_xor_b32_e32 v3, 16, v14
	v_add_u32_e32 v15, 64, v15
	v_cmp_lt_i32_e32 vcc, v3, v15
	v_xor_b32_e32 v18, 32, v14
	s_lshl_b32 s4, s26, 9
	v_cndmask_b32_e32 v3, v14, v3, vcc
	v_lshlrev_b32_e32 v3, 2, v3
	v_cmp_lt_i32_e32 vcc, v18, v15
	s_add_i32 s4, s4, 0
	v_mov_b32_e32 v17, v12
	s_nop 1
	v_permlane16_swap_b32_e32 v17, v12
	v_add_f32_e32 v15, v12, v17
	v_cndmask_b32_e32 v14, v14, v18, vcc
	v_lshlrev_b32_e32 v14, 2, v14
	v_mov_b32_e32 v17, v15
	s_nop 1
	v_permlane32_swap_b32_e32 v17, v15
	v_add_f32_e32 v15, v15, v17
	v_cmp_gt_u32_e32 vcc, 16, v16
	v_lshl_add_u32 v12, v16, 2, s4
	s_and_saveexec_b64 s[4:5], vcc
	s_cbranch_execz .LBB0_23
	ds_write_b32 v12, v15 offset:32768
; template <int LO, int HI> __global__ void __launch_bounds__(NWAVES * 64, 2) fox_fwd(Args args) {
;     ...
;             for (int b = 0; b < 8; ++b) { acc[b] += __shfl_xor(acc[b], 16); acc[b] += __shfl_xor(acc[b], 32); if (lane < 16) red[(wave * 8 + b) * 16 + lane] = acc[b]; }
.LBB0_23:
	s_or_b64 exec, exec, s[4:5]
	v_mov_b32_e32 v15, v13
	s_nop 1
	v_permlane16_swap_b32_e32 v15, v13
	v_add_f32_e32 v13, v13, v15
	v_mov_b32_e32 v15, v13
	s_nop 1
	v_permlane32_swap_b32_e32 v15, v13
	v_add_f32_e32 v13, v13, v15
	s_and_saveexec_b64 s[4:5], vcc
	s_cbranch_execz .LBB0_25
	ds_write_b32 v12, v13 offset:32832
.LBB0_25:
	s_or_b64 exec, exec, s[4:5]
	v_mov_b32_e32 v13, v10
	s_nop 1
	v_permlane16_swap_b32_e32 v13, v10
	v_add_f32_e32 v10, v10, v13
	v_mov_b32_e32 v13, v10
	s_nop 1
	v_permlane32_swap_b32_e32 v13, v10
	v_add_f32_e32 v10, v10, v13
	s_and_saveexec_b64 s[4:5], vcc
	s_cbranch_execz .LBB0_27
	ds_write_b32 v12, v10 offset:32896
.LBB0_27:
	s_or_b64 exec, exec, s[4:5]
	v_mov_b32_e32 v10, v11
	s_nop 1
	v_permlane16_swap_b32_e32 v10, v11
	v_add_f32_e32 v10, v11, v10
	v_mov_b32_e32 v11, v10
	s_nop 1
	v_permlane32_swap_b32_e32 v11, v10
	v_add_f32_e32 v10, v10, v11
	s_and_saveexec_b64 s[4:5], vcc
	s_cbranch_execz .LBB0_29
	ds_write_b32 v12, v10 offset:32960
.LBB0_29:
	s_or_b64 exec, exec, s[4:5]
	v_mov_b32_e32 v10, v8
	s_nop 1
	v_permlane16_swap_b32_e32 v10, v8
	v_add_f32_e32 v8, v8, v10
	v_mov_b32_e32 v10, v8
	s_nop 1
	v_permlane32_swap_b32_e32 v10, v8
	v_add_f32_e32 v8, v8, v10
	s_and_saveexec_b64 s[4:5], vcc
	s_cbranch_execz .LBB0_31
	ds_write_b32 v12, v8 offset:33024
.LBB0_31:
	s_or_b64 exec, exec, s[4:5]
	v_mov_b32_e32 v8, v9
	s_nop 1
	v_permlane16_swap_b32_e32 v8, v9
	v_add_f32_e32 v8, v9, v8
	v_mov_b32_e32 v9, v8
	s_nop 1
	v_permlane32_swap_b32_e32 v9, v8
	v_add_f32_e32 v8, v8, v9
	s_and_saveexec_b64 s[4:5], vcc
	s_cbranch_execz .LBB0_33
	ds_write_b32 v12, v8 offset:33088
.LBB0_33:
	s_or_b64 exec, exec, s[4:5]
	v_mov_b32_e32 v8, v6
	s_nop 1
	v_permlane16_swap_b32_e32 v8, v6
	v_add_f32_e32 v6, v6, v8
	v_mov_b32_e32 v8, v6
	s_nop 1
	v_permlane32_swap_b32_e32 v8, v6
	v_add_f32_e32 v6, v6, v8
	s_and_saveexec_b64 s[4:5], vcc
	s_cbranch_execz .LBB0_35
	ds_write_b32 v12, v6 offset:33152
.LBB0_35:
	s_or_b64 exec, exec, s[4:5]
	v_mov_b32_e32 v3, v7
	s_nop 1
	v_permlane16_swap_b32_e32 v3, v7
	v_add_f32_e32 v3, v7, v3
	v_mov_b32_e32 v6, v3
	s_nop 1
	v_permlane32_swap_b32_e32 v6, v3
	v_add_f32_e32 v3, v3, v6
	s_and_saveexec_b64 s[4:5], vcc
	s_cbranch_execz .LBB0_37
	ds_write_b32 v12, v3 offset:33216
